# P6 final output stores marked nt (streaming)
# baseline (speedup 1.0000x reference)
.LBB0_2232:
	s_or_b64 exec, exec, s[4:5]
	s_waitcnt vmcnt(0) lgkmcnt(0)
	s_barrier
	s_mov_b32 s98, 0xaaaaaaaa
	s_mov_b32 s99, 0xaaaaaaaa
	v_mov_b32_e32 v244, 0xfffff010
	v_mov_b32_e32 v245, 0x1000
	v_cndmask_b32_e64 v240, 0, v244, s[98:99]
	v_cndmask_b32_e64 v241, 0, -1, s[98:99]
	v_cndmask_b32_e64 v242, v245, 16, s[98:99]
	v_mov_b32_e32 v243, 0
	v_lshl_add_u64 v[0:1], v[194:195], 2, s[76:77]
	global_load_dwordx4 v[12:15], v[0:1], off
	global_load_dwordx4 v[8:11], v[0:1], off offset:16
	global_load_dwordx4 v[4:7], v[0:1], off offset:512
	s_waitcnt lgkmcnt(0)
	global_load_dwordx4 v[0:3], v[0:1], off offset:528
	v_lshl_add_u32 v84, v199, 2, 0
	v_add_u32_e32 v142, 0x1000, v84
	v_add_u32_e32 v76, s21, v199
	ds_read2_b32 v[88:89], v142 offset1:16
	v_mov_b32_e32 v77, s12
	v_add_u32_e32 v84, 16, v76
	v_add_u32_e32 v86, 32, v76
	ds_read2_b32 v[134:135], v142 offset0:32 offset1:48
	v_or3_b32 v82, s20, v202, v77
	v_ashrrev_i32_e32 v77, 31, v76
	v_ashrrev_i32_e32 v85, 31, v84
	v_ashrrev_i32_e32 v87, 31, v86
	v_or3_b32 v83, 0, 0, s13
	v_lshlrev_b64 v[90:91], 12, v[76:77]
	v_lshlrev_b64 v[84:85], 12, v[84:85]
	v_lshlrev_b64 v[86:87], 12, v[86:87]
	v_lshlrev_b64 v[82:83], 2, v[82:83]
	v_lshl_add_u64 v[90:91], s[78:79], 0, v[90:91]
	v_lshl_add_u64 v[84:85], s[78:79], 0, v[84:85]
	v_lshl_add_u64 v[86:87], s[78:79], 0, v[86:87]
	v_lshl_add_u64 v[136:137], v[90:91], 0, v[82:83]
	v_lshl_add_u64 v[138:139], v[84:85], 0, v[82:83]
	v_lshl_add_u64 v[140:141], v[86:87], 0, v[82:83]
	s_waitcnt lgkmcnt(1)
	v_pk_mul_f32 v[84:85], v[130:131], v[88:89] op_sel_hi:[1,0]
	v_pk_mul_f32 v[86:87], v[132:133], v[88:89] op_sel_hi:[1,0]
	v_pk_mul_f32 v[92:93], v[126:127], v[88:89] op_sel_hi:[1,0]
	v_pk_mul_f32 v[90:91], v[128:129], v[88:89] op_sel_hi:[1,0]
	v_pk_mul_f32 v[96:97], v[122:123], v[88:89] op_sel_hi:[1,0]
	v_pk_mul_f32 v[94:95], v[124:125], v[88:89] op_sel_hi:[1,0]
	v_pk_mul_f32 v[100:101], v[118:119], v[88:89] op_sel_hi:[1,0]
	v_pk_mul_f32 v[98:99], v[120:121], v[88:89] op_sel_hi:[1,0]
	v_mov_b32_e32 v88, v89
	s_waitcnt lgkmcnt(0)
	v_pk_mul_f32 v[116:117], v[174:175], v[134:135] op_sel_hi:[1,0]
	v_pk_mul_f32 v[118:119], v[176:177], v[134:135] op_sel_hi:[1,0]
	v_pk_mul_f32 v[120:121], v[170:171], v[134:135] op_sel_hi:[1,0]
	v_pk_mul_f32 v[122:123], v[172:173], v[134:135] op_sel_hi:[1,0]
	v_pk_mul_f32 v[104:105], v[190:191], v[88:89] op_sel_hi:[1,0]
	v_pk_mul_f32 v[102:103], v[192:193], v[88:89] op_sel_hi:[1,0]
	v_pk_mul_f32 v[108:109], v[186:187], v[88:89] op_sel_hi:[1,0]
	v_pk_mul_f32 v[106:107], v[188:189], v[88:89] op_sel_hi:[1,0]
	v_pk_mul_f32 v[112:113], v[182:183], v[88:89] op_sel_hi:[1,0]
	v_pk_mul_f32 v[110:111], v[184:185], v[88:89] op_sel_hi:[1,0]
	v_pk_mul_f32 v[126:127], v[178:179], v[88:89] op_sel_hi:[1,0]
	v_pk_mul_f32 v[114:115], v[180:181], v[88:89] op_sel_hi:[1,0]
	v_pk_mul_f32 v[124:125], v[166:167], v[134:135] op_sel_hi:[1,0]
	s_waitcnt vmcnt(3)
	v_pk_mul_f32 v[86:87], v[14:15], v[86:87]
	v_pk_mul_f32 v[84:85], v[12:13], v[84:85]
	s_waitcnt vmcnt(2)
	v_pk_mul_f32 v[90:91], v[10:11], v[90:91]
	v_pk_mul_f32 v[88:89], v[8:9], v[92:93]
	s_waitcnt vmcnt(1)
	v_pk_mul_f32 v[94:95], v[6:7], v[94:95]
	v_pk_mul_f32 v[92:93], v[4:5], v[96:97]
	s_waitcnt vmcnt(0)
	v_pk_mul_f32 v[98:99], v[2:3], v[98:99]
	v_pk_mul_f32 v[96:97], v[0:1], v[100:101]
	v_pk_mul_f32 v[102:103], v[14:15], v[102:103]
	v_pk_mul_f32 v[100:101], v[12:13], v[104:105]
	v_pk_mul_f32 v[106:107], v[10:11], v[106:107]
	v_pk_mul_f32 v[104:105], v[8:9], v[108:109]
	v_pk_mul_f32 v[110:111], v[6:7], v[110:111]
	v_pk_mul_f32 v[108:109], v[4:5], v[112:113]
	v_pk_mul_f32 v[114:115], v[2:3], v[114:115]
	v_pk_mul_f32 v[112:113], v[0:1], v[126:127]
	v_pk_mul_f32 v[118:119], v[14:15], v[118:119]
	v_pk_mul_f32 v[116:117], v[12:13], v[116:117]
	v_pk_mul_f32 v[122:123], v[10:11], v[122:123]
	v_pk_mul_f32 v[120:121], v[8:9], v[120:121]
	v_mov_b32_e32 v204, v84
	v_mov_b32_e32 v205, v85
	v_mov_b32_e32 v206, v86
	v_mov_b32_e32 v207, v87
	v_cndmask_b32_e64 v220, v88, v204, s[98:99]
	v_cndmask_b32_e64 v221, v89, v205, s[98:99]
	v_cndmask_b32_e64 v222, v90, v206, s[98:99]
	v_cndmask_b32_e64 v223, v91, v207, s[98:99]
	v_mov_b32_dpp v220, v220 quad_perm:[1,0,3,2] row_mask:0xf bank_mask:0xf
	v_mov_b32_dpp v221, v221 quad_perm:[1,0,3,2] row_mask:0xf bank_mask:0xf
	v_mov_b32_dpp v222, v222 quad_perm:[1,0,3,2] row_mask:0xf bank_mask:0xf
	v_mov_b32_dpp v223, v223 quad_perm:[1,0,3,2] row_mask:0xf bank_mask:0xf
	v_lshl_add_u64 v[224:225], v[136:137], 0, v[240:241]
	v_lshl_add_u64 v[226:227], v[136:137], 0, v[242:243]
	v_cndmask_b32_e64 v204, v204, v220, s[98:99]
	v_cndmask_b32_e64 v205, v205, v221, s[98:99]
	v_cndmask_b32_e64 v206, v206, v222, s[98:99]
	v_cndmask_b32_e64 v207, v207, v223, s[98:99]
	v_cndmask_b32_e64 v88, v220, v88, s[98:99]
	v_cndmask_b32_e64 v89, v221, v89, s[98:99]
	v_cndmask_b32_e64 v90, v222, v90, s[98:99]
	v_cndmask_b32_e64 v91, v223, v91, s[98:99]
	global_store_dwordx4 v[224:225], v[204:207], off nt
	global_store_dwordx4 v[226:227], v[88:91], off nt
	s_nop 1
	v_mov_b32_e32 v208, v92
	v_mov_b32_e32 v209, v93
	v_mov_b32_e32 v210, v94
	v_mov_b32_e32 v211, v95
	v_cndmask_b32_e64 v220, v96, v208, s[98:99]
	v_cndmask_b32_e64 v221, v97, v209, s[98:99]
	v_cndmask_b32_e64 v222, v98, v210, s[98:99]
	v_cndmask_b32_e64 v223, v99, v211, s[98:99]
	v_mov_b32_dpp v220, v220 quad_perm:[1,0,3,2] row_mask:0xf bank_mask:0xf
	v_mov_b32_dpp v221, v221 quad_perm:[1,0,3,2] row_mask:0xf bank_mask:0xf
	v_mov_b32_dpp v222, v222 quad_perm:[1,0,3,2] row_mask:0xf bank_mask:0xf
	v_mov_b32_dpp v223, v223 quad_perm:[1,0,3,2] row_mask:0xf bank_mask:0xf
	v_lshl_add_u64 v[224:225], v[136:137], 0, v[240:241]
	v_lshl_add_u64 v[226:227], v[136:137], 0, v[242:243]
	v_cndmask_b32_e64 v208, v208, v220, s[98:99]
	v_cndmask_b32_e64 v209, v209, v221, s[98:99]
	v_cndmask_b32_e64 v210, v210, v222, s[98:99]
	v_cndmask_b32_e64 v211, v211, v223, s[98:99]
	v_cndmask_b32_e64 v96, v220, v96, s[98:99]
	v_cndmask_b32_e64 v97, v221, v97, s[98:99]
	v_cndmask_b32_e64 v98, v222, v98, s[98:99]
	v_cndmask_b32_e64 v99, v223, v99, s[98:99]
	global_store_dwordx4 v[224:225], v[208:211], off offset:512 nt
	global_store_dwordx4 v[226:227], v[96:99], off offset:512 nt
	s_nop 1
	v_mov_b32_e32 v212, v100
	v_mov_b32_e32 v213, v101
	v_mov_b32_e32 v214, v102
	v_mov_b32_e32 v215, v103
	v_cndmask_b32_e64 v220, v104, v212, s[98:99]
	v_cndmask_b32_e64 v221, v105, v213, s[98:99]
	v_cndmask_b32_e64 v222, v106, v214, s[98:99]
	v_cndmask_b32_e64 v223, v107, v215, s[98:99]
	v_mov_b32_dpp v220, v220 quad_perm:[1,0,3,2] row_mask:0xf bank_mask:0xf
	v_mov_b32_dpp v221, v221 quad_perm:[1,0,3,2] row_mask:0xf bank_mask:0xf
	v_mov_b32_dpp v222, v222 quad_perm:[1,0,3,2] row_mask:0xf bank_mask:0xf
	v_mov_b32_dpp v223, v223 quad_perm:[1,0,3,2] row_mask:0xf bank_mask:0xf
	v_lshl_add_u64 v[224:225], v[138:139], 0, v[240:241]
	v_lshl_add_u64 v[226:227], v[138:139], 0, v[242:243]
	v_cndmask_b32_e64 v212, v212, v220, s[98:99]
	v_cndmask_b32_e64 v213, v213, v221, s[98:99]
	v_cndmask_b32_e64 v214, v214, v222, s[98:99]
	v_cndmask_b32_e64 v215, v215, v223, s[98:99]
	v_cndmask_b32_e64 v104, v220, v104, s[98:99]
	v_cndmask_b32_e64 v105, v221, v105, s[98:99]
	v_cndmask_b32_e64 v106, v222, v106, s[98:99]
	v_cndmask_b32_e64 v107, v223, v107, s[98:99]
	global_store_dwordx4 v[224:225], v[212:215], off nt
	global_store_dwordx4 v[226:227], v[104:107], off nt
	s_nop 1
	v_mov_b32_e32 v216, v108
	v_mov_b32_e32 v217, v109
	v_mov_b32_e32 v218, v110
	v_mov_b32_e32 v219, v111
	v_cndmask_b32_e64 v220, v112, v216, s[98:99]
	v_cndmask_b32_e64 v221, v113, v217, s[98:99]
	v_cndmask_b32_e64 v222, v114, v218, s[98:99]
	v_cndmask_b32_e64 v223, v115, v219, s[98:99]
	v_mov_b32_dpp v220, v220 quad_perm:[1,0,3,2] row_mask:0xf bank_mask:0xf
	v_mov_b32_dpp v221, v221 quad_perm:[1,0,3,2] row_mask:0xf bank_mask:0xf
	v_mov_b32_dpp v222, v222 quad_perm:[1,0,3,2] row_mask:0xf bank_mask:0xf
	v_mov_b32_dpp v223, v223 quad_perm:[1,0,3,2] row_mask:0xf bank_mask:0xf
	v_lshl_add_u64 v[224:225], v[138:139], 0, v[240:241]
	v_lshl_add_u64 v[226:227], v[138:139], 0, v[242:243]
	v_cndmask_b32_e64 v216, v216, v220, s[98:99]
	v_cndmask_b32_e64 v217, v217, v221, s[98:99]
	v_cndmask_b32_e64 v218, v218, v222, s[98:99]
	v_cndmask_b32_e64 v219, v219, v223, s[98:99]
	v_cndmask_b32_e64 v112, v220, v112, s[98:99]
	v_cndmask_b32_e64 v113, v221, v113, s[98:99]
	v_cndmask_b32_e64 v114, v222, v114, s[98:99]
	v_cndmask_b32_e64 v115, v223, v115, s[98:99]
	global_store_dwordx4 v[224:225], v[216:219], off offset:512 nt
	global_store_dwordx4 v[226:227], v[112:115], off offset:512 nt
	s_nop 1
	v_mov_b32_e32 v204, v116
	v_mov_b32_e32 v205, v117
	v_mov_b32_e32 v206, v118
	v_mov_b32_e32 v207, v119
	v_cndmask_b32_e64 v220, v120, v204, s[98:99]
	v_cndmask_b32_e64 v221, v121, v205, s[98:99]
	v_cndmask_b32_e64 v222, v122, v206, s[98:99]
	v_cndmask_b32_e64 v223, v123, v207, s[98:99]
	v_mov_b32_dpp v220, v220 quad_perm:[1,0,3,2] row_mask:0xf bank_mask:0xf
	v_mov_b32_dpp v221, v221 quad_perm:[1,0,3,2] row_mask:0xf bank_mask:0xf
	v_mov_b32_dpp v222, v222 quad_perm:[1,0,3,2] row_mask:0xf bank_mask:0xf
	v_mov_b32_dpp v223, v223 quad_perm:[1,0,3,2] row_mask:0xf bank_mask:0xf
	v_lshl_add_u64 v[224:225], v[140:141], 0, v[240:241]
	v_lshl_add_u64 v[226:227], v[140:141], 0, v[242:243]
	v_cndmask_b32_e64 v204, v204, v220, s[98:99]
	v_cndmask_b32_e64 v205, v205, v221, s[98:99]
	v_cndmask_b32_e64 v206, v206, v222, s[98:99]
	v_cndmask_b32_e64 v207, v207, v223, s[98:99]
	v_cndmask_b32_e64 v120, v220, v120, s[98:99]
	v_cndmask_b32_e64 v121, v221, v121, s[98:99]
	v_cndmask_b32_e64 v122, v222, v122, s[98:99]
	v_cndmask_b32_e64 v123, v223, v123, s[98:99]
	global_store_dwordx4 v[224:225], v[204:207], off nt
	global_store_dwordx4 v[226:227], v[120:123], off nt
	s_nop 1
	v_pk_mul_f32 v[84:85], v[168:169], v[134:135] op_sel_hi:[1,0]
	v_add_u32_e32 v88, 48, v76
	v_pk_mul_f32 v[86:87], v[6:7], v[84:85]
	v_pk_mul_f32 v[84:85], v[4:5], v[124:125]
	v_mov_b32_e32 v208, v84
	v_mov_b32_e32 v209, v85
	v_mov_b32_e32 v210, v86
	v_mov_b32_e32 v211, v87
	v_ashrrev_i32_e32 v89, 31, v88
	v_mov_b32_e32 v90, v135
	v_pk_mul_f32 v[84:85], v[162:163], v[134:135] op_sel_hi:[1,0]
	v_pk_mul_f32 v[86:87], v[164:165], v[134:135] op_sel_hi:[1,0]
	v_pk_mul_f32 v[84:85], v[0:1], v[84:85]
	v_pk_mul_f32 v[86:87], v[2:3], v[86:87]
	v_lshlrev_b64 v[88:89], 12, v[88:89]
	v_cndmask_b32_e64 v220, v84, v208, s[98:99]
	v_cndmask_b32_e64 v221, v85, v209, s[98:99]
	v_cndmask_b32_e64 v222, v86, v210, s[98:99]
	v_cndmask_b32_e64 v223, v87, v211, s[98:99]
	v_mov_b32_dpp v220, v220 quad_perm:[1,0,3,2] row_mask:0xf bank_mask:0xf
	v_mov_b32_dpp v221, v221 quad_perm:[1,0,3,2] row_mask:0xf bank_mask:0xf
	v_mov_b32_dpp v222, v222 quad_perm:[1,0,3,2] row_mask:0xf bank_mask:0xf
	v_mov_b32_dpp v223, v223 quad_perm:[1,0,3,2] row_mask:0xf bank_mask:0xf
	v_lshl_add_u64 v[224:225], v[140:141], 0, v[240:241]
	v_lshl_add_u64 v[226:227], v[140:141], 0, v[242:243]
	v_cndmask_b32_e64 v208, v208, v220, s[98:99]
	v_cndmask_b32_e64 v209, v209, v221, s[98:99]
	v_cndmask_b32_e64 v210, v210, v222, s[98:99]
	v_cndmask_b32_e64 v211, v211, v223, s[98:99]
	v_cndmask_b32_e64 v84, v220, v84, s[98:99]
	v_cndmask_b32_e64 v85, v221, v85, s[98:99]
	v_cndmask_b32_e64 v86, v222, v86, s[98:99]
	v_cndmask_b32_e64 v87, v223, v87, s[98:99]
	global_store_dwordx4 v[224:225], v[208:211], off offset:512 nt
	global_store_dwordx4 v[226:227], v[84:87], off offset:512 nt
	s_nop 1
	v_lshl_add_u64 v[88:89], s[78:79], 0, v[88:89]
	v_lshl_add_u64 v[88:89], v[88:89], 0, v[82:83]
	v_pk_mul_f32 v[84:85], v[158:159], v[90:91] op_sel_hi:[1,0]
	v_pk_mul_f32 v[86:87], v[160:161], v[90:91] op_sel_hi:[1,0]
	v_pk_mul_f32 v[84:85], v[12:13], v[84:85]
	v_pk_mul_f32 v[86:87], v[14:15], v[86:87]
	v_mov_b32_e32 v212, v84
	v_mov_b32_e32 v213, v85
	v_mov_b32_e32 v214, v86
	v_mov_b32_e32 v215, v87
	s_nop 1
	v_pk_mul_f32 v[84:85], v[154:155], v[90:91] op_sel_hi:[1,0]
	v_pk_mul_f32 v[86:87], v[156:157], v[90:91] op_sel_hi:[1,0]
	v_pk_mul_f32 v[84:85], v[8:9], v[84:85]
	v_pk_mul_f32 v[86:87], v[10:11], v[86:87]
	v_cndmask_b32_e64 v220, v84, v212, s[98:99]
	v_cndmask_b32_e64 v221, v85, v213, s[98:99]
	v_cndmask_b32_e64 v222, v86, v214, s[98:99]
	v_cndmask_b32_e64 v223, v87, v215, s[98:99]
	v_mov_b32_dpp v220, v220 quad_perm:[1,0,3,2] row_mask:0xf bank_mask:0xf
	v_mov_b32_dpp v221, v221 quad_perm:[1,0,3,2] row_mask:0xf bank_mask:0xf
	v_mov_b32_dpp v222, v222 quad_perm:[1,0,3,2] row_mask:0xf bank_mask:0xf
	v_mov_b32_dpp v223, v223 quad_perm:[1,0,3,2] row_mask:0xf bank_mask:0xf
	v_lshl_add_u64 v[224:225], v[88:89], 0, v[240:241]
	v_lshl_add_u64 v[226:227], v[88:89], 0, v[242:243]
	v_cndmask_b32_e64 v212, v212, v220, s[98:99]
	v_cndmask_b32_e64 v213, v213, v221, s[98:99]
	v_cndmask_b32_e64 v214, v214, v222, s[98:99]
	v_cndmask_b32_e64 v215, v215, v223, s[98:99]
	v_cndmask_b32_e64 v84, v220, v84, s[98:99]
	v_cndmask_b32_e64 v85, v221, v85, s[98:99]
	v_cndmask_b32_e64 v86, v222, v86, s[98:99]
	v_cndmask_b32_e64 v87, v223, v87, s[98:99]
	global_store_dwordx4 v[224:225], v[212:215], off nt
	global_store_dwordx4 v[226:227], v[84:87], off nt
	s_nop 1
	s_nop 1
	v_pk_mul_f32 v[84:85], v[150:151], v[90:91] op_sel_hi:[1,0]
	v_pk_mul_f32 v[86:87], v[152:153], v[90:91] op_sel_hi:[1,0]
	v_pk_mul_f32 v[84:85], v[4:5], v[84:85]
	v_pk_mul_f32 v[86:87], v[6:7], v[86:87]
	v_mov_b32_e32 v216, v84
	v_mov_b32_e32 v217, v85
	v_mov_b32_e32 v218, v86
	v_mov_b32_e32 v219, v87
	s_nop 1
	v_pk_mul_f32 v[84:85], v[146:147], v[90:91] op_sel_hi:[1,0]
	v_pk_mul_f32 v[86:87], v[148:149], v[90:91] op_sel_hi:[1,0]
	ds_read2_b32 v[90:91], v142 offset0:128 offset1:144
	v_pk_mul_f32 v[86:87], v[2:3], v[86:87]
	v_pk_mul_f32 v[84:85], v[0:1], v[84:85]
	v_cndmask_b32_e64 v220, v84, v216, s[98:99]
	v_cndmask_b32_e64 v221, v85, v217, s[98:99]
	v_cndmask_b32_e64 v222, v86, v218, s[98:99]
	v_cndmask_b32_e64 v223, v87, v219, s[98:99]
	v_mov_b32_dpp v220, v220 quad_perm:[1,0,3,2] row_mask:0xf bank_mask:0xf
	v_mov_b32_dpp v221, v221 quad_perm:[1,0,3,2] row_mask:0xf bank_mask:0xf
	v_mov_b32_dpp v222, v222 quad_perm:[1,0,3,2] row_mask:0xf bank_mask:0xf
	v_mov_b32_dpp v223, v223 quad_perm:[1,0,3,2] row_mask:0xf bank_mask:0xf
	v_lshl_add_u64 v[224:225], v[88:89], 0, v[240:241]
	v_lshl_add_u64 v[226:227], v[88:89], 0, v[242:243]
	v_cndmask_b32_e64 v216, v216, v220, s[98:99]
	v_cndmask_b32_e64 v217, v217, v221, s[98:99]
	v_cndmask_b32_e64 v218, v218, v222, s[98:99]
	v_cndmask_b32_e64 v219, v219, v223, s[98:99]
	v_cndmask_b32_e64 v84, v220, v84, s[98:99]
	v_cndmask_b32_e64 v85, v221, v85, s[98:99]
	v_cndmask_b32_e64 v86, v222, v86, s[98:99]
	v_cndmask_b32_e64 v87, v223, v87, s[98:99]
	global_store_dwordx4 v[224:225], v[216:219], off offset:512 nt
	global_store_dwordx4 v[226:227], v[84:87], off offset:512 nt
	s_nop 1
	s_waitcnt lgkmcnt(0)
	v_pk_mul_f32 v[50:51], v[50:51], v[90:91] op_sel_hi:[1,0]
	v_add_u32_e32 v84, 0x80, v76
	v_ashrrev_i32_e32 v85, 31, v84
	v_lshlrev_b64 v[84:85], 12, v[84:85]
	v_lshl_add_u64 v[84:85], s[78:79], 0, v[84:85]
	v_pk_mul_f32 v[52:53], v[52:53], v[90:91] op_sel_hi:[1,0]
	v_lshl_add_u64 v[84:85], v[84:85], 0, v[82:83]
	v_pk_mul_f32 v[52:53], v[2:3], v[52:53]
	v_pk_mul_f32 v[50:51], v[0:1], v[50:51]
	v_mov_b32_e32 v204, v50
	v_mov_b32_e32 v205, v51
	v_mov_b32_e32 v206, v52
	v_mov_b32_e32 v207, v53
	v_pk_mul_f32 v[62:63], v[62:63], v[90:91] op_sel_hi:[1,0]
	v_pk_mul_f32 v[64:65], v[64:65], v[90:91] op_sel_hi:[1,0]
	v_add_u32_e32 v50, 0x90, v76
	v_ashrrev_i32_e32 v51, 31, v50
	v_mov_b32_e32 v52, v91
	v_lshlrev_b64 v[50:51], 12, v[50:51]
	v_lshl_add_u64 v[50:51], s[78:79], 0, v[50:51]
	v_pk_mul_f32 v[38:39], v[38:39], v[52:53] op_sel_hi:[1,0]
	v_pk_mul_f32 v[40:41], v[40:41], v[52:53] op_sel_hi:[1,0]
	v_lshl_add_u64 v[50:51], v[50:51], 0, v[82:83]
	v_pk_mul_f32 v[40:41], v[6:7], v[40:41]
	v_pk_mul_f32 v[38:39], v[4:5], v[38:39]
	v_mov_b32_e32 v208, v38
	v_mov_b32_e32 v209, v39
	v_mov_b32_e32 v210, v40
	v_mov_b32_e32 v211, v41
	v_pk_mul_f32 v[34:35], v[34:35], v[52:53] op_sel_hi:[1,0]
	v_pk_mul_f32 v[36:37], v[36:37], v[52:53] op_sel_hi:[1,0]
	ds_read2_b32 v[38:39], v142 offset0:160 offset1:176
	v_pk_mul_f32 v[36:37], v[2:3], v[36:37]
	v_pk_mul_f32 v[34:35], v[0:1], v[34:35]
	v_cndmask_b32_e64 v220, v34, v208, s[98:99]
	v_cndmask_b32_e64 v221, v35, v209, s[98:99]
	v_cndmask_b32_e64 v222, v36, v210, s[98:99]
	v_cndmask_b32_e64 v223, v37, v211, s[98:99]
	v_mov_b32_dpp v220, v220 quad_perm:[1,0,3,2] row_mask:0xf bank_mask:0xf
	v_mov_b32_dpp v221, v221 quad_perm:[1,0,3,2] row_mask:0xf bank_mask:0xf
	v_mov_b32_dpp v222, v222 quad_perm:[1,0,3,2] row_mask:0xf bank_mask:0xf
	v_mov_b32_dpp v223, v223 quad_perm:[1,0,3,2] row_mask:0xf bank_mask:0xf
	v_lshl_add_u64 v[224:225], v[50:51], 0, v[240:241]
	v_lshl_add_u64 v[226:227], v[50:51], 0, v[242:243]
	v_cndmask_b32_e64 v208, v208, v220, s[98:99]
	v_cndmask_b32_e64 v209, v209, v221, s[98:99]
	v_cndmask_b32_e64 v210, v210, v222, s[98:99]
	v_cndmask_b32_e64 v211, v211, v223, s[98:99]
	v_cndmask_b32_e64 v34, v220, v34, s[98:99]
	v_cndmask_b32_e64 v35, v221, v35, s[98:99]
	v_cndmask_b32_e64 v36, v222, v36, s[98:99]
	v_cndmask_b32_e64 v37, v223, v37, s[98:99]
	global_store_dwordx4 v[224:225], v[208:211], off offset:512 nt
	global_store_dwordx4 v[226:227], v[34:37], off offset:512 nt
	s_nop 1
	v_pk_mul_f32 v[46:47], v[46:47], v[52:53] op_sel_hi:[1,0]
	s_waitcnt lgkmcnt(0)
	v_pk_mul_f32 v[18:19], v[18:19], v[38:39] op_sel_hi:[1,0]
	v_add_u32_e32 v34, 0xa0, v76
	v_ashrrev_i32_e32 v35, 31, v34
	v_lshlrev_b64 v[34:35], 12, v[34:35]
	v_lshl_add_u64 v[34:35], s[78:79], 0, v[34:35]
	v_pk_mul_f32 v[20:21], v[20:21], v[38:39] op_sel_hi:[1,0]
	v_lshl_add_u64 v[34:35], v[34:35], 0, v[82:83]
	v_pk_mul_f32 v[20:21], v[2:3], v[20:21]
	v_pk_mul_f32 v[18:19], v[0:1], v[18:19]
	v_mov_b32_e32 v212, v18
	v_mov_b32_e32 v213, v19
	v_mov_b32_e32 v214, v20
	v_mov_b32_e32 v215, v21
	v_pk_mul_f32 v[22:23], v[22:23], v[38:39] op_sel_hi:[1,0]
	v_pk_mul_f32 v[24:25], v[24:25], v[38:39] op_sel_hi:[1,0]
	v_add_u32_e32 v18, 0xb0, v76
	v_ashrrev_i32_e32 v19, 31, v18
	v_pk_mul_f32 v[24:25], v[6:7], v[24:25]
	v_pk_mul_f32 v[22:23], v[4:5], v[22:23]
	v_mov_b32_e32 v20, v39
	v_lshlrev_b64 v[18:19], 12, v[18:19]
	v_pk_mul_f32 v[48:49], v[48:49], v[52:53] op_sel_hi:[1,0]
	v_pk_mul_f32 v[30:31], v[30:31], v[38:39] op_sel_hi:[1,0]
	v_pk_mul_f32 v[32:33], v[32:33], v[38:39] op_sel_hi:[1,0]
	v_cndmask_b32_e64 v220, v212, v22, s[98:99]
	v_cndmask_b32_e64 v221, v213, v23, s[98:99]
	v_cndmask_b32_e64 v222, v214, v24, s[98:99]
	v_cndmask_b32_e64 v223, v215, v25, s[98:99]
	v_mov_b32_dpp v220, v220 quad_perm:[1,0,3,2] row_mask:0xf bank_mask:0xf
	v_mov_b32_dpp v221, v221 quad_perm:[1,0,3,2] row_mask:0xf bank_mask:0xf
	v_mov_b32_dpp v222, v222 quad_perm:[1,0,3,2] row_mask:0xf bank_mask:0xf
	v_mov_b32_dpp v223, v223 quad_perm:[1,0,3,2] row_mask:0xf bank_mask:0xf
	v_lshl_add_u64 v[224:225], v[34:35], 0, v[240:241]
	v_lshl_add_u64 v[226:227], v[34:35], 0, v[242:243]
	v_cndmask_b32_e64 v22, v22, v220, s[98:99]
	v_cndmask_b32_e64 v23, v23, v221, s[98:99]
	v_cndmask_b32_e64 v24, v24, v222, s[98:99]
	v_cndmask_b32_e64 v25, v25, v223, s[98:99]
	v_cndmask_b32_e64 v212, v220, v212, s[98:99]
	v_cndmask_b32_e64 v213, v221, v213, s[98:99]
	v_cndmask_b32_e64 v214, v222, v214, s[98:99]
	v_cndmask_b32_e64 v215, v223, v215, s[98:99]
	global_store_dwordx4 v[224:225], v[22:25], off offset:512 nt
	global_store_dwordx4 v[226:227], v[212:215], off offset:512 nt
	s_nop 1
	v_lshl_add_u64 v[18:19], s[78:79], 0, v[18:19]
	v_pk_mul_f32 v[64:65], v[14:15], v[64:65]
	v_pk_mul_f32 v[22:23], v[78:79], v[20:21] op_sel_hi:[1,0]
	v_pk_mul_f32 v[24:25], v[80:81], v[20:21] op_sel_hi:[1,0]
	v_pk_mul_f32 v[62:63], v[12:13], v[62:63]
	v_pk_mul_f32 v[48:49], v[14:15], v[48:49]
	v_pk_mul_f32 v[46:47], v[12:13], v[46:47]
	v_pk_mul_f32 v[32:33], v[14:15], v[32:33]
	v_pk_mul_f32 v[30:31], v[12:13], v[30:31]
	v_pk_mul_f32 v[14:15], v[14:15], v[24:25]
	v_pk_mul_f32 v[12:13], v[12:13], v[22:23]
	v_lshl_add_u64 v[18:19], v[18:19], 0, v[82:83]
	v_pk_mul_f32 v[58:59], v[58:59], v[90:91] op_sel_hi:[1,0]
	v_pk_mul_f32 v[60:61], v[60:61], v[90:91] op_sel_hi:[1,0]
	v_pk_mul_f32 v[42:43], v[42:43], v[52:53] op_sel_hi:[1,0]
	v_pk_mul_f32 v[44:45], v[44:45], v[52:53] op_sel_hi:[1,0]
	v_pk_mul_f32 v[26:27], v[26:27], v[38:39] op_sel_hi:[1,0]
	v_pk_mul_f32 v[28:29], v[28:29], v[38:39] op_sel_hi:[1,0]
	v_mov_b32_e32 v216, v12
	v_mov_b32_e32 v217, v13
	v_mov_b32_e32 v218, v14
	v_mov_b32_e32 v219, v15
	v_pk_mul_f32 v[60:61], v[10:11], v[60:61]
	v_pk_mul_f32 v[58:59], v[8:9], v[58:59]
	v_pk_mul_f32 v[12:13], v[74:75], v[20:21] op_sel_hi:[1,0]
	v_pk_mul_f32 v[14:15], v[16:17], v[20:21] op_sel_hi:[1,0]
	v_pk_mul_f32 v[44:45], v[10:11], v[44:45]
	v_pk_mul_f32 v[42:43], v[8:9], v[42:43]
	v_pk_mul_f32 v[28:29], v[10:11], v[28:29]
	v_pk_mul_f32 v[26:27], v[8:9], v[26:27]
	v_pk_mul_f32 v[10:11], v[10:11], v[14:15]
	v_pk_mul_f32 v[8:9], v[8:9], v[12:13]
	v_pk_mul_f32 v[54:55], v[54:55], v[90:91] op_sel_hi:[1,0]
	v_pk_mul_f32 v[56:57], v[56:57], v[90:91] op_sel_hi:[1,0]
	v_cndmask_b32_e64 v220, v8, v216, s[98:99]
	v_cndmask_b32_e64 v221, v9, v217, s[98:99]
	v_cndmask_b32_e64 v222, v10, v218, s[98:99]
	v_cndmask_b32_e64 v223, v11, v219, s[98:99]
	v_mov_b32_dpp v220, v220 quad_perm:[1,0,3,2] row_mask:0xf bank_mask:0xf
	v_mov_b32_dpp v221, v221 quad_perm:[1,0,3,2] row_mask:0xf bank_mask:0xf
	v_mov_b32_dpp v222, v222 quad_perm:[1,0,3,2] row_mask:0xf bank_mask:0xf
	v_mov_b32_dpp v223, v223 quad_perm:[1,0,3,2] row_mask:0xf bank_mask:0xf
	v_lshl_add_u64 v[224:225], v[18:19], 0, v[240:241]
	v_lshl_add_u64 v[226:227], v[18:19], 0, v[242:243]
	v_cndmask_b32_e64 v216, v216, v220, s[98:99]
	v_cndmask_b32_e64 v217, v217, v221, s[98:99]
	v_cndmask_b32_e64 v218, v218, v222, s[98:99]
	v_cndmask_b32_e64 v219, v219, v223, s[98:99]
	v_cndmask_b32_e64 v8, v220, v8, s[98:99]
	v_cndmask_b32_e64 v9, v221, v9, s[98:99]
	v_cndmask_b32_e64 v10, v222, v10, s[98:99]
	v_cndmask_b32_e64 v11, v223, v11, s[98:99]
	global_store_dwordx4 v[224:225], v[216:219], off nt
	global_store_dwordx4 v[226:227], v[8:11], off nt
	s_nop 1
	v_pk_mul_f32 v[56:57], v[6:7], v[56:57]
	v_pk_mul_f32 v[54:55], v[4:5], v[54:55]
	v_pk_mul_f32 v[8:9], v[70:71], v[20:21] op_sel_hi:[1,0]
	v_pk_mul_f32 v[10:11], v[72:73], v[20:21] op_sel_hi:[1,0]
	v_pk_mul_f32 v[4:5], v[4:5], v[8:9]
	v_pk_mul_f32 v[6:7], v[6:7], v[10:11]
	v_mov_b32_e32 v208, v4
	v_mov_b32_e32 v209, v5
	v_mov_b32_e32 v210, v6
	v_mov_b32_e32 v211, v7
	v_mov_b32_e32 v212, v62
	v_mov_b32_e32 v213, v63
	v_mov_b32_e32 v214, v64
	v_mov_b32_e32 v215, v65
	v_cndmask_b32_e64 v220, v58, v212, s[98:99]
	v_cndmask_b32_e64 v221, v59, v213, s[98:99]
	v_cndmask_b32_e64 v222, v60, v214, s[98:99]
	v_cndmask_b32_e64 v223, v61, v215, s[98:99]
	v_mov_b32_dpp v220, v220 quad_perm:[1,0,3,2] row_mask:0xf bank_mask:0xf
	v_mov_b32_dpp v221, v221 quad_perm:[1,0,3,2] row_mask:0xf bank_mask:0xf
	v_mov_b32_dpp v222, v222 quad_perm:[1,0,3,2] row_mask:0xf bank_mask:0xf
	v_mov_b32_dpp v223, v223 quad_perm:[1,0,3,2] row_mask:0xf bank_mask:0xf
	v_lshl_add_u64 v[224:225], v[84:85], 0, v[240:241]
	v_lshl_add_u64 v[226:227], v[84:85], 0, v[242:243]
	v_cndmask_b32_e64 v212, v212, v220, s[98:99]
	v_cndmask_b32_e64 v213, v213, v221, s[98:99]
	v_cndmask_b32_e64 v214, v214, v222, s[98:99]
	v_cndmask_b32_e64 v215, v215, v223, s[98:99]
	v_cndmask_b32_e64 v58, v220, v58, s[98:99]
	v_cndmask_b32_e64 v59, v221, v59, s[98:99]
	v_cndmask_b32_e64 v60, v222, v60, s[98:99]
	v_cndmask_b32_e64 v61, v223, v61, s[98:99]
	global_store_dwordx4 v[224:225], v[212:215], off nt
	global_store_dwordx4 v[226:227], v[58:61], off nt
	s_nop 1
	v_pk_mul_f32 v[4:5], v[66:67], v[20:21] op_sel_hi:[1,0]
	v_pk_mul_f32 v[6:7], v[68:69], v[20:21] op_sel_hi:[1,0]
	v_pk_mul_f32 v[0:1], v[0:1], v[4:5]
	v_pk_mul_f32 v[2:3], v[2:3], v[6:7]
	v_cndmask_b32_e64 v220, v204, v54, s[98:99]
	v_cndmask_b32_e64 v221, v205, v55, s[98:99]
	v_cndmask_b32_e64 v222, v206, v56, s[98:99]
	v_cndmask_b32_e64 v223, v207, v57, s[98:99]
	v_mov_b32_dpp v220, v220 quad_perm:[1,0,3,2] row_mask:0xf bank_mask:0xf
	v_mov_b32_dpp v221, v221 quad_perm:[1,0,3,2] row_mask:0xf bank_mask:0xf
	v_mov_b32_dpp v222, v222 quad_perm:[1,0,3,2] row_mask:0xf bank_mask:0xf
	v_mov_b32_dpp v223, v223 quad_perm:[1,0,3,2] row_mask:0xf bank_mask:0xf
	v_lshl_add_u64 v[224:225], v[84:85], 0, v[240:241]
	v_lshl_add_u64 v[226:227], v[84:85], 0, v[242:243]
	v_cndmask_b32_e64 v54, v54, v220, s[98:99]
	v_cndmask_b32_e64 v55, v55, v221, s[98:99]
	v_cndmask_b32_e64 v56, v56, v222, s[98:99]
	v_cndmask_b32_e64 v57, v57, v223, s[98:99]
	v_cndmask_b32_e64 v204, v220, v204, s[98:99]
	v_cndmask_b32_e64 v205, v221, v205, s[98:99]
	v_cndmask_b32_e64 v206, v222, v206, s[98:99]
	v_cndmask_b32_e64 v207, v223, v207, s[98:99]
	global_store_dwordx4 v[224:225], v[54:57], off offset:512 nt
	global_store_dwordx4 v[226:227], v[204:207], off offset:512 nt
	s_nop 1
	v_mov_b32_e32 v216, v46
	v_mov_b32_e32 v217, v47
	v_mov_b32_e32 v218, v48
	v_mov_b32_e32 v219, v49
	v_cndmask_b32_e64 v220, v42, v216, s[98:99]
	v_cndmask_b32_e64 v221, v43, v217, s[98:99]
	v_cndmask_b32_e64 v222, v44, v218, s[98:99]
	v_cndmask_b32_e64 v223, v45, v219, s[98:99]
	v_mov_b32_dpp v220, v220 quad_perm:[1,0,3,2] row_mask:0xf bank_mask:0xf
	v_mov_b32_dpp v221, v221 quad_perm:[1,0,3,2] row_mask:0xf bank_mask:0xf
	v_mov_b32_dpp v222, v222 quad_perm:[1,0,3,2] row_mask:0xf bank_mask:0xf
	v_mov_b32_dpp v223, v223 quad_perm:[1,0,3,2] row_mask:0xf bank_mask:0xf
	v_lshl_add_u64 v[224:225], v[50:51], 0, v[240:241]
	v_lshl_add_u64 v[226:227], v[50:51], 0, v[242:243]
	v_cndmask_b32_e64 v216, v216, v220, s[98:99]
	v_cndmask_b32_e64 v217, v217, v221, s[98:99]
	v_cndmask_b32_e64 v218, v218, v222, s[98:99]
	v_cndmask_b32_e64 v219, v219, v223, s[98:99]
	v_cndmask_b32_e64 v42, v220, v42, s[98:99]
	v_cndmask_b32_e64 v43, v221, v43, s[98:99]
	v_cndmask_b32_e64 v44, v222, v44, s[98:99]
	v_cndmask_b32_e64 v45, v223, v45, s[98:99]
	global_store_dwordx4 v[224:225], v[216:219], off nt
	global_store_dwordx4 v[226:227], v[42:45], off nt
	s_nop 1
	v_mov_b32_e32 v212, v30
	v_mov_b32_e32 v213, v31
	v_mov_b32_e32 v214, v32
	v_mov_b32_e32 v215, v33
	v_cndmask_b32_e64 v220, v26, v212, s[98:99]
	v_cndmask_b32_e64 v221, v27, v213, s[98:99]
	v_cndmask_b32_e64 v222, v28, v214, s[98:99]
	v_cndmask_b32_e64 v223, v29, v215, s[98:99]
	v_mov_b32_dpp v220, v220 quad_perm:[1,0,3,2] row_mask:0xf bank_mask:0xf
	v_mov_b32_dpp v221, v221 quad_perm:[1,0,3,2] row_mask:0xf bank_mask:0xf
	v_mov_b32_dpp v222, v222 quad_perm:[1,0,3,2] row_mask:0xf bank_mask:0xf
	v_mov_b32_dpp v223, v223 quad_perm:[1,0,3,2] row_mask:0xf bank_mask:0xf
	v_lshl_add_u64 v[224:225], v[34:35], 0, v[240:241]
	v_lshl_add_u64 v[226:227], v[34:35], 0, v[242:243]
	v_cndmask_b32_e64 v212, v212, v220, s[98:99]
	v_cndmask_b32_e64 v213, v213, v221, s[98:99]
	v_cndmask_b32_e64 v214, v214, v222, s[98:99]
	v_cndmask_b32_e64 v215, v215, v223, s[98:99]
	v_cndmask_b32_e64 v26, v220, v26, s[98:99]
	v_cndmask_b32_e64 v27, v221, v27, s[98:99]
	v_cndmask_b32_e64 v28, v222, v28, s[98:99]
	v_cndmask_b32_e64 v29, v223, v29, s[98:99]
	global_store_dwordx4 v[224:225], v[212:215], off nt
	global_store_dwordx4 v[226:227], v[26:29], off nt
	s_nop 1
	v_cndmask_b32_e64 v220, v0, v208, s[98:99]
	v_cndmask_b32_e64 v221, v1, v209, s[98:99]
	v_cndmask_b32_e64 v222, v2, v210, s[98:99]
	v_cndmask_b32_e64 v223, v3, v211, s[98:99]
	v_mov_b32_dpp v220, v220 quad_perm:[1,0,3,2] row_mask:0xf bank_mask:0xf
	v_mov_b32_dpp v221, v221 quad_perm:[1,0,3,2] row_mask:0xf bank_mask:0xf
	v_mov_b32_dpp v222, v222 quad_perm:[1,0,3,2] row_mask:0xf bank_mask:0xf
	v_mov_b32_dpp v223, v223 quad_perm:[1,0,3,2] row_mask:0xf bank_mask:0xf
	v_lshl_add_u64 v[224:225], v[18:19], 0, v[240:241]
	v_lshl_add_u64 v[226:227], v[18:19], 0, v[242:243]
	v_cndmask_b32_e64 v208, v208, v220, s[98:99]
	v_cndmask_b32_e64 v209, v209, v221, s[98:99]
	v_cndmask_b32_e64 v210, v210, v222, s[98:99]
	v_cndmask_b32_e64 v211, v211, v223, s[98:99]
	v_cndmask_b32_e64 v0, v220, v0, s[98:99]
	v_cndmask_b32_e64 v1, v221, v1, s[98:99]
	v_cndmask_b32_e64 v2, v222, v2, s[98:99]
	v_cndmask_b32_e64 v3, v223, v3, s[98:99]
	global_store_dwordx4 v[224:225], v[208:211], off offset:512 nt
	global_store_dwordx4 v[226:227], v[0:3], off offset:512 nt
	s_nop 1
